# byte-phase experiment: whole instruction stream shifted by 4 bytes (one s_nop 0 at entry) relative to the final candidate
# speedup vs baseline: 1.0073x; 1.0073x over previous
_Z10hybrid_fwd4Args:
	s_nop 0
	s_load_dwordx2 s[80:81], s[0:1], 0x80
	s_load_dwordx2 s[86:87], s[0:1], 0x90
	s_mov_b32 s93, s2
	s_add_u32 s2, s0, 0x90
	s_addc_u32 s3, s1, 0
	v_and_b32_e32 v212, 0x3ff, v0
	s_waitcnt lgkmcnt(0)
	s_and_b32 s4, s86, 7
	v_readfirstlane_b32 s85, v212
	s_cmp_lg_u32 s4, 0
	s_mov_b32 s84, s93
	s_cbranch_scc1 .LBB0_2
	s_ashr_i32 s5, s93, 31
	s_lshr_b32 s5, s5, 29
	s_add_i32 s5, s93, s5
	s_and_b32 s6, s5, -8
	s_ashr_i32 s4, s86, 3
	s_sub_i32 s6, s93, s6
	s_mul_i32 s4, s4, s6
	s_ashr_i32 s5, s5, 3
	s_add_i32 s84, s4, s5
